# one static s_setprio 1 for waves 4-7 across the attention tile loop (reset at unit end), on top of the PV-pipelined attention
# speedup vs baseline: 1.0112x; 1.0040x over previous
.LBB0_561:
	v_mov_b32_e32 v5, v0
	v_mov_b32_e32 v3, v115
	v_readfirstlane_b32 s11, v5
	s_ashr_i32 s33, s11, 6
	s_lshl_b32 s9, s33, 5
	s_add_i32 s0, s9, s10
	s_ashr_i32 s1, s0, 31
	s_lshl_b64 s[74:75], s[0:1], 11
	s_lshl_b64 s[4:5], s[0:1], 12
	s_add_u32 s1, s68, s4
	s_addc_u32 s4, s69, s5
	s_lshl_b32 s91, s6, 7
	s_lshl_b32 s5, s6, 8
	s_add_u32 s1, s1, s5
	s_addc_u32 s5, s4, 0
	s_lshl_b32 s4, s86, 7
	v_and_b32_e32 v130, 31, v5
	s_add_u32 s4, s1, s4
	v_bfe_u32 v8, v5, 5, 1
	s_addc_u32 s5, s5, 0
	v_lshlrev_b32_e32 v2, 12, v130
	v_lshl_add_u64 v[6:7], s[4:5], 0, v[2:3]
	v_lshlrev_b32_e32 v2, 4, v8
	v_lshl_add_u64 v[6:7], v[6:7], 0, v[2:3]
	global_load_dwordx4 v[98:101], v[6:7], off
	global_load_dwordx4 v[102:105], v[6:7], off offset:32
	global_load_dwordx4 v[106:109], v[6:7], off offset:64
	global_load_dwordx4 v[110:113], v[6:7], off offset:96
	v_mul_f32_e32 v3, 0x4f800000, v4
	v_cmp_gt_f32_e32 vcc, s18, v4
	v_lshlrev_b32_e32 v10, 2, v8
	v_lshlrev_b32_e32 v131, 10, v8
	v_cndmask_b32_e32 v3, v4, v3, vcc
	v_sqrt_f32_e32 v4, v3
	v_lshlrev_b32_e32 v8, 4, v130
	v_add3_u32 v132, 0, v131, v8
	s_waitcnt vmcnt(0)
	v_add_u32_e32 v8, -1, v4
	v_add_u32_e32 v11, 1, v4
	v_fma_f32 v12, -v8, v4, v3
	v_fma_f32 v13, -v11, v4, v3
	v_cmp_ge_f32_e64 s[4:5], 0, v12
	s_mov_b32 s7, s85
	s_or_b32 s84, s84, s86
	v_cndmask_b32_e64 v4, v4, v8, s[4:5]
	v_cmp_lt_f32_e64 s[4:5], 0, v13
	s_lshl_b32 s12, s33, 9
	s_and_b32 s14, s11, 0x3fffffc0
	v_cndmask_b32_e64 v4, v4, v11, s[4:5]
	v_mul_f32_e32 v8, 0x37800000, v4
	v_cndmask_b32_e32 v4, v4, v8, vcc
	v_cmp_class_f32_e32 vcc, v3, v124
	s_lshl_b64 s[6:7], s[6:7], 22
	s_lshl_b64 s[4:5], s[84:85], 21
	v_cndmask_b32_e32 v3, v4, v3, vcc
	s_ashr_i32 s13, s12, 31
	v_readlane_b32 s16, v244, 9
	v_readlane_b32 s17, v244, 10
	s_add_u32 s1, s16, s6
	s_addc_u32 s11, s17, s7
	s_lshl_b64 s[6:7], s[12:13], 1
	s_add_u32 s12, s1, s6
	s_addc_u32 s13, s11, s7
	s_lshl_b32 s15, s33, 10
	s_addk_i32 s10, 0x100
	s_add_i32 s76, s15, s90
	s_lshr_b32 s1, s10, 6
	v_and_b32_e32 v6, 63, v5
	v_bfe_u32 v116, v5, 4, 2
	v_lshlrev_b32_e32 v7, 1, v5
	v_lshlrev_b32_e32 v9, 3, v5
	v_and_b32_e32 v129, 15, v5
	v_bfe_u32 v5, v5, 2, 2
	s_add_u32 s4, s62, s4
	v_or_b32_e32 v5, v10, v5
	s_addc_u32 s5, s63, s5
	s_add_u32 s4, s4, s6
	v_lshlrev_b32_e32 v114, 4, v6
	s_addc_u32 s5, s5, s7
	v_lshl_add_u64 v[122:123], s[4:5], 0, v[114:115]
	s_add_i32 s84, s1, -4
	s_add_i32 s77, s15, 0
	s_lshl_b32 s6, s14, 2
	v_lshl_add_u64 v[118:119], s[12:13], 0, v[114:115]
	s_mov_b64 s[10:11], 0x2000
	s_add_i32 s6, s6, 0
	v_lshl_add_u64 v[120:121], v[118:119], 0, s[10:11]
	s_add_i32 s10, s6, 0x12000
	s_add_i32 s88, s77, 0x8000
	v_and_b32_e32 v9, 24, v9
	v_add_u32_e32 v114, s10, v2
	s_mov_b64 s[94:95], s[68:69]
	s_sub_i32 s89, s1, s8
	s_mov_b64 s[96:97], s[62:63]
	s_waitcnt vmcnt(3)
	s_nop 0
	v_and_b32_e32 v8, 0xffff0000, v98
	v_lshlrev_b32_e32 v4, 16, v98
	v_mul_f32_e32 v8, v8, v8
	v_lshlrev_b32_e32 v11, 16, v99
	v_fmac_f32_e32 v8, v4, v4
	v_and_b32_e32 v12, 0xffff0000, v99
	v_fmac_f32_e32 v8, v11, v11
	v_lshlrev_b32_e32 v13, 16, v100
	v_fmac_f32_e32 v8, v12, v12
	v_and_b32_e32 v14, 0xffff0000, v100
	v_fmac_f32_e32 v8, v13, v13
	v_lshlrev_b32_e32 v15, 16, v101
	v_fmac_f32_e32 v8, v14, v14
	v_and_b32_e32 v16, 0xffff0000, v101
	v_fmac_f32_e32 v8, v15, v15
	s_waitcnt vmcnt(2)
	v_fmac_f32_e32 v8, v16, v16
	v_lshlrev_b32_e32 v4, 16, v102
	v_fmac_f32_e32 v8, v4, v4
	v_and_b32_e32 v4, 0xffff0000, v102
	v_fmac_f32_e32 v8, v4, v4
	v_lshlrev_b32_e32 v4, 16, v103
	v_fmac_f32_e32 v8, v4, v4
	v_and_b32_e32 v4, 0xffff0000, v103
	v_fmac_f32_e32 v8, v4, v4
	v_lshlrev_b32_e32 v4, 16, v104
	v_fmac_f32_e32 v8, v4, v4
	v_and_b32_e32 v4, 0xffff0000, v104
	v_fmac_f32_e32 v8, v4, v4
	v_lshlrev_b32_e32 v4, 16, v105
	v_fmac_f32_e32 v8, v4, v4
	v_and_b32_e32 v4, 0xffff0000, v105
	s_waitcnt vmcnt(1)
	v_fmac_f32_e32 v8, v4, v4
	v_lshlrev_b32_e32 v4, 16, v106
	v_fmac_f32_e32 v8, v4, v4
	v_and_b32_e32 v4, 0xffff0000, v106
	v_fmac_f32_e32 v8, v4, v4
	v_lshlrev_b32_e32 v4, 16, v107
	v_fmac_f32_e32 v8, v4, v4
	v_and_b32_e32 v4, 0xffff0000, v107
	v_fmac_f32_e32 v8, v4, v4
	v_lshlrev_b32_e32 v4, 16, v108
	v_fmac_f32_e32 v8, v4, v4
	v_and_b32_e32 v4, 0xffff0000, v108
	v_fmac_f32_e32 v8, v4, v4
	v_lshlrev_b32_e32 v4, 16, v109
	v_fmac_f32_e32 v8, v4, v4
	v_and_b32_e32 v4, 0xffff0000, v109
	s_waitcnt vmcnt(0)
	v_fmac_f32_e32 v8, v4, v4
	v_lshlrev_b32_e32 v4, 16, v110
	v_fmac_f32_e32 v8, v4, v4
	v_and_b32_e32 v4, 0xffff0000, v110
	v_fmac_f32_e32 v8, v4, v4
	v_lshlrev_b32_e32 v4, 16, v111
	v_fmac_f32_e32 v8, v4, v4
	v_and_b32_e32 v4, 0xffff0000, v111
	v_fmac_f32_e32 v8, v4, v4
	v_lshlrev_b32_e32 v4, 16, v112
	v_fmac_f32_e32 v8, v4, v4
	v_and_b32_e32 v4, 0xffff0000, v112
	v_fmac_f32_e32 v8, v4, v4
	v_lshlrev_b32_e32 v4, 16, v113
	v_fmac_f32_e32 v8, v4, v4
	v_and_b32_e32 v4, 0xffff0000, v113
	v_fmac_f32_e32 v8, v4, v4
	v_mov_b32_e32 v4, v8
	s_nop 1
	v_permlane32_swap_b32_e32 v8, v4
	v_add_f32_e32 v4, v8, v4
	v_mul_f32_e32 v8, 0x4f800000, v4
	v_cmp_gt_f32_e32 vcc, s18, v4
	v_lshlrev_b32_e32 v11, 6, v5
	v_and_or_b32 v2, v7, 32, v11
	v_cndmask_b32_e32 v4, v4, v8, vcc
	v_sqrt_f32_e32 v8, v4
	v_add3_u32 v152, v9, s90, v2
	v_or_b32_e32 v2, s9, v130
	v_sub_u32_e32 v153, 0xbf, v2
	v_add_u32_e32 v5, -1, v8
	v_fma_f32 v12, -v5, v8, v4
	v_cmp_ge_f32_e64 s[4:5], 0, v12
	v_add_u32_e32 v12, 1, v8
	v_mov_b32_e32 v2, 0
	v_cndmask_b32_e64 v5, v8, v5, s[4:5]
	v_fma_f32 v8, -v12, v8, v4
	v_cmp_lt_f32_e64 s[4:5], 0, v8
	v_mov_b32_e32 v16, v2
	v_mov_b32_e32 v17, v2
	v_cndmask_b32_e64 v5, v5, v12, s[4:5]
	v_mul_f32_e32 v8, 0x37800000, v5
	v_cndmask_b32_e32 v5, v5, v8, vcc
	v_cmp_class_f32_e32 vcc, v4, v124
	s_lshl_b64 s[4:5], s[84:85], 13
	v_mov_b32_e32 v7, v2
	v_cndmask_b32_e32 v4, v5, v4, vcc
	v_mul_f32_e32 v3, v3, v4
	v_lshl_add_u64 v[4:5], v[122:123], 0, s[4:5]
	s_mov_b32 s4, m0
	s_mov_b32 m0, s77
	s_nop 0
	global_load_lds_dwordx4 v[4:5], off
	s_mov_b32 m0, s4
	s_lshl_b64 s[4:5], s[84:85], 14
	v_lshl_add_u64 v[4:5], v[118:119], 0, s[4:5]
	s_mov_b32 s6, m0
	s_mov_b32 m0, s76
	s_nop 0
	global_load_lds_dwordx4 v[4:5], off
	s_mov_b32 m0, s6
	v_lshl_add_u64 v[4:5], v[120:121], 0, s[4:5]
	s_mov_b32 s4, m0
	s_mov_b32 m0, s88
	s_nop 0
	global_load_lds_dwordx4 v[4:5], off
	s_mov_b32 m0, s4
	s_add_i32 s4, s1, -3
	s_mov_b32 s5, s85
	s_lshl_b64 s[6:7], s[4:5], 13
	v_lshl_add_u64 v[4:5], v[122:123], 0, s[6:7]
	s_add_i32 s6, s77, 0x2000
	s_mov_b32 s7, m0
	s_mov_b32 m0, s6
	s_nop 0
	global_load_lds_dwordx4 v[4:5], off
	s_mov_b32 m0, s7
	s_lshl_b64 s[4:5], s[4:5], 14
	v_lshl_add_u64 v[4:5], v[118:119], 0, s[4:5]
	s_add_i32 s6, s77, 0xa000
	s_mov_b32 s7, m0
	s_mov_b32 m0, s6
	s_nop 0
	global_load_lds_dwordx4 v[4:5], off
	s_mov_b32 m0, s7
	v_lshl_add_u64 v[4:5], v[120:121], 0, s[4:5]
	s_add_i32 s4, s77, 0xc000
	s_mov_b32 s5, m0
	s_mov_b32 m0, s4
	s_nop 0
	global_load_lds_dwordx4 v[4:5], off
	s_mov_b32 m0, s5
	v_fmamk_f32 v150, v3, 0x3f8020c5, v125
	v_or_b32_e32 v3, s0, v130
	s_lshl_b32 s0, s33, 2
	s_add_i32 s68, s0, 0
	v_sub_u32_e32 v151, v10, v3
	v_cmp_gt_u32_e64 s[4:5], 32, v6
	v_cmp_eq_u32_e64 s[6:7], 0, v6
	v_mov_b32_e32 v3, v2
	v_mov_b32_e32 v4, v2
	v_mov_b32_e32 v5, v2
	v_mov_b32_e32 v6, v2
	v_mov_b32_e32 v8, v2
	v_mov_b32_e32 v9, v2
	v_mov_b32_e32 v10, v2
	v_mov_b32_e32 v11, v2
	v_mov_b32_e32 v12, v2
	v_mov_b32_e32 v13, v2
	v_mov_b32_e32 v14, v2
	v_mov_b32_e32 v15, v2
	v_mov_b64_e32 v[64:65], v[16:17]
	v_mov_b64_e32 v[48:49], v[16:17]
	v_mov_b64_e32 v[32:33], v[16:17]
	v_mul_f32_e32 v133, 0, v117
	v_add_f32_e32 v134, v117, v117
	v_mul_f32_e32 v135, 0x40400000, v117
	v_mul_f32_e32 v136, 0x41000000, v117
	v_mul_f32_e32 v137, 0x41100000, v117
	v_mul_f32_e32 v138, 0x41200000, v117
	v_mul_f32_e32 v139, 0x41300000, v117
	v_mul_f32_e32 v140, 0x41800000, v117
	v_mul_f32_e32 v141, 0x41880000, v117
	v_mul_f32_e32 v142, 0x41900000, v117
	v_mul_f32_e32 v143, 0x41980000, v117
	v_mul_f32_e32 v144, 0x41c00000, v117
	v_mul_f32_e32 v145, 0x41c80000, v117
	v_mul_f32_e32 v146, 0x41d00000, v117
	v_mul_f32_e32 v148, 0x41d80000, v117
	v_mul_f32_e32 v149, 0x42000000, v117
	v_mov_b32_e32 v190, v133
	v_mov_b32_e32 v191, v117
	v_mov_b32_e32 v216, v146
	v_mov_b32_e32 v217, v148
	s_add_i32 s68, s68, 0x22800
	v_lshl_add_u32 v147, v130, 2, s10
	s_max_i32 s69, s89, 0
	s_mov_b32 s80, 0
	v_mov_b64_e32 v[62:63], v[14:15]
	v_mov_b64_e32 v[60:61], v[12:13]
	v_mov_b64_e32 v[58:59], v[10:11]
	v_mov_b64_e32 v[56:57], v[8:9]
	v_mov_b64_e32 v[54:55], v[6:7]
	v_mov_b64_e32 v[52:53], v[4:5]
	v_mov_b64_e32 v[50:51], v[2:3]
	v_mov_b64_e32 v[46:47], v[14:15]
	v_mov_b64_e32 v[44:45], v[12:13]
	v_mov_b64_e32 v[42:43], v[10:11]
	v_mov_b64_e32 v[40:41], v[8:9]
	v_mov_b64_e32 v[38:39], v[6:7]
	v_mov_b64_e32 v[36:37], v[4:5]
	v_mov_b64_e32 v[34:35], v[2:3]
	v_mov_b64_e32 v[30:31], v[14:15]
	v_mov_b64_e32 v[28:29], v[12:13]
	v_mov_b64_e32 v[26:27], v[10:11]
	v_mov_b64_e32 v[24:25], v[8:9]
	v_mov_b64_e32 v[22:23], v[6:7]
	v_mov_b64_e32 v[20:21], v[4:5]
	v_mov_b64_e32 v[18:19], v[2:3]
	s_mov_b32 s83, 0
	s_mov_b32 s81, 0
	v_readfirstlane_b32 s99, v0
	s_nop 3
	s_bitcmp1_b32 s99, 8
	s_cbranch_scc0 .Lprio_np
	s_setprio 1
.Lprio_np:
	v_mov_b32_e32 v154, v2
	v_mov_b32_e32 v155, v2
	s_cmp_eq_u32 s69, s83
	s_cbranch_scc0 .LBB0_563

.LBB0_589:
	s_setprio 0
	v_mov_b32_e32 v66, v154
	s_nop 1
	v_permlane32_swap_b32_e32 v154, v66
	s_and_saveexec_b64 s[0:1], s[4:5]
	s_cbranch_execz .LBB0_552
	v_add_f32_e32 v66, v154, v66
	ds_write_b32 v147, v66 offset:128
	s_branch .LBB0_552
